# c13p_rms_reduction_dpp_permlane16
# speedup vs baseline: 1.0201x; 1.0042x over previous
.LBB0_1477:
	v_rcp_f32_e32 v113, v80
	v_rcp_f32_e32 v112, v81
	v_rcp_f32_e32 v111, v82
	v_rcp_f32_e32 v110, v83
	v_rcp_f32_e32 v109, v12
	v_rcp_f32_e32 v108, v13
	v_rcp_f32_e32 v107, v14
	v_rcp_f32_e32 v106, v15
	v_rcp_f32_e32 v105, v8
	v_rcp_f32_e32 v104, v9
	v_rcp_f32_e32 v103, v10
	v_rcp_f32_e32 v102, v11
	v_rcp_f32_e32 v101, v4
	v_rcp_f32_e32 v100, v5
	v_rcp_f32_e32 v99, v6
	v_rcp_f32_e32 v98, v7
	v_mov_b32_e32 v4, v203
	s_mov_b64 s[4:5], -1
	v_ashrrev_i32_e32 v5, 31, v4
	v_lshl_add_u64 v[0:1], v[4:5], 2, s[8:9]
	s_and_b64 vcc, exec, s[48:49]
	s_cbranch_vccz .LBB0_1479
	s_mov_b32 s100, 0xffff0000
	s_mov_b32 s101, 0xffff0000
	s_mov_b32 s4, 0x8000
	v_add_co_u32_e32 v6, vcc, s4, v0
	s_mov_b32 s4, 0x10000
	s_nop 0
	v_addc_co_u32_e32 v7, vcc, 0, v1, vcc
	v_add_co_u32_e32 v118, vcc, s74, v0
	global_load_dword v5, v[0:1], off
	s_nop 0
	v_addc_co_u32_e32 v119, vcc, 0, v1, vcc
	v_add_co_u32_e32 v8, vcc, s4, v0
	s_mov_b32 s4, 0x18000
	s_nop 0
	v_addc_co_u32_e32 v9, vcc, 0, v1, vcc
	v_add_co_u32_e32 v120, vcc, s73, v0
	global_load_dword v140, v[118:119], off offset:-4096
	s_nop 0
	v_addc_co_u32_e32 v121, vcc, 0, v1, vcc
	v_add_co_u32_e32 v10, vcc, s4, v0
	global_load_dword v130, v[120:121], off offset:-4096
	s_nop 0
	v_addc_co_u32_e32 v11, vcc, 0, v1, vcc
	v_add_co_u32_e32 v122, vcc, s72, v0
	s_movk_i32 s4, 0x1000
	s_nop 0
	v_addc_co_u32_e32 v123, vcc, 0, v1, vcc
	global_load_dword v114, v[122:123], off offset:-4096
	global_load_dword v115, v[10:11], off offset:2048
	global_load_dword v131, v[8:9], off offset:2048
	global_load_dword v142, v[6:7], off offset:2048
	s_nop 0
	global_load_dword v8, v[0:1], off offset:2048
	v_add_co_u32_e32 v124, vcc, s4, v0
	s_movk_i32 s4, 0x2000
	s_nop 0
	v_addc_co_u32_e32 v125, vcc, 0, v1, vcc
	v_add_co_u32_e32 v6, vcc, s4, v0
	global_load_dword v116, v[122:123], off
	global_load_dword v132, v[120:121], off
	global_load_dword v143, v[118:119], off
	v_addc_co_u32_e32 v7, vcc, 0, v1, vcc
	global_load_dword v9, v[6:7], off offset:-4096
	global_load_dword v117, v[122:123], off offset:2048
	global_load_dword v133, v[120:121], off offset:2048
	global_load_dword v146, v[118:119], off offset:2048
	global_load_dword v10, v[124:125], off offset:2048
	v_add_co_u32_e32 v120, vcc, s75, v0
	v_mul_f32_e64 v12, v112, -v204
	s_nop 0
	v_addc_co_u32_e32 v121, vcc, 0, v1, vcc
	v_add_co_u32_e32 v122, vcc, s84, v0
	v_mul_f32_e64 v14, v109, -v204
	s_nop 0
	v_addc_co_u32_e32 v123, vcc, 0, v1, vcc
	v_add_co_u32_e32 v124, vcc, s76, v0
	s_movk_i32 s4, 0x4000
	s_nop 0
	v_addc_co_u32_e32 v125, vcc, 0, v1, vcc
	v_add_co_u32_e32 v126, vcc, s79, v0
	v_mul_f32_e64 v80, v108, -v204
	s_nop 0
	v_addc_co_u32_e32 v127, vcc, 0, v1, vcc
	v_add_co_u32_e32 v138, vcc, s77, v0
	v_mul_f32_e64 v82, v107, -v204
	s_nop 0
	v_addc_co_u32_e32 v139, vcc, 0, v1, vcc
	v_add_co_u32_e32 v144, vcc, s78, v0
	v_mul_f32_e64 v84, v106, -v204
	s_nop 0
	v_addc_co_u32_e32 v145, vcc, 0, v1, vcc
	v_mul_f32_e64 v86, v105, -v204
	v_mul_f32_e64 v88, v104, -v204
	v_mul_f32_e64 v90, v103, -v204
	v_mul_f32_e64 v92, v102, -v204
	v_mul_f32_e64 v94, v101, -v204
	v_mul_f32_e64 v96, v100, -v204
	v_mul_f32_e64 v129, v99, -v204
	v_mul_f32_e64 v2, v113, -v204
	v_mul_f32_e64 v134, v98, -v204
	v_mul_f32_e64 v15, v111, -v204
	v_mul_f32_e64 v83, v110, -v204
	global_load_dword v155, v[122:123], off offset:-4096
	global_load_dword v136, v[126:127], off offset:-4096
	global_load_dword v119, v[144:145], off offset:-4096
	v_lshlrev_b32_e32 v245, 2, v203
	s_add_u32 s98, s8, 0x3000
	s_addc_u32 s99, s9, 0
	global_load_dword v184, v245, s[98:99] offset:-4096
	global_load_dword v190, v245, s[98:99] offset:-2048
	global_load_dword v194, v245, s[98:99]
	global_load_dword v212, v245, s[98:99] offset:2048
	s_add_u32 s98, s8, 0x5000
	s_addc_u32 s99, s9, 0
	global_load_dword v215, v245, s[98:99] offset:-4096
	global_load_dword v220, v245, s[98:99] offset:-2048
	global_load_dword v224, v245, s[98:99]
	global_load_dword v229, v245, s[98:99] offset:2048
	s_add_u32 s98, s8, 0x7000
	s_addc_u32 s99, s9, 0
	global_load_dword v233, v245, s[98:99] offset:-4096
	global_load_dword v237, v245, s[98:99] offset:-2048
	global_load_dword v241, v245, s[98:99]
	global_load_dword v247, v245, s[98:99] offset:2048
	s_add_u32 s98, s8, 0xb000
	s_addc_u32 s99, s9, 0
	global_load_dword v189, v245, s[98:99] offset:-2048
	global_load_dword v193, v245, s[98:99]
	global_load_dword v197, v245, s[98:99] offset:2048
	s_add_u32 s98, s8, 0xd000
	s_addc_u32 s99, s9, 0
	global_load_dword v213, v245, s[98:99] offset:-4096
	global_load_dword v219, v245, s[98:99] offset:-2048
	global_load_dword v223, v245, s[98:99]
	global_load_dword v227, v245, s[98:99] offset:2048
	s_add_u32 s98, s8, 0xf000
	s_addc_u32 s99, s9, 0
	global_load_dword v230, v245, s[98:99] offset:-4096
	global_load_dword v236, v245, s[98:99] offset:-2048
	global_load_dword v240, v245, s[98:99]
	global_load_dword v246, v245, s[98:99] offset:2048
	s_add_u32 s98, s8, 0x13000
	s_addc_u32 s99, s9, 0
	global_load_dword v188, v245, s[98:99] offset:-2048
	global_load_dword v192, v245, s[98:99]
	global_load_dword v196, v245, s[98:99] offset:2048
	s_add_u32 s98, s8, 0x15000
	s_addc_u32 s99, s9, 0
	global_load_dword v214, v245, s[98:99] offset:-4096
	global_load_dword v218, v245, s[98:99] offset:-2048
	global_load_dword v222, v245, s[98:99]
	global_load_dword v226, v245, s[98:99] offset:2048
	s_add_u32 s98, s8, 0x17000
	s_addc_u32 s99, s9, 0
	global_load_dword v231, v245, s[98:99] offset:-4096
	global_load_dword v235, v245, s[98:99] offset:-2048
	global_load_dword v239, v245, s[98:99]
	global_load_dword v243, v245, s[98:99] offset:2048
	s_add_u32 s98, s8, 0x1b000
	s_addc_u32 s99, s9, 0
	global_load_dword v185, v245, s[98:99] offset:-2048
	global_load_dword v191, v245, s[98:99]
	global_load_dword v195, v245, s[98:99] offset:2048
	s_add_u32 s98, s8, 0x1d000
	s_addc_u32 s99, s9, 0
	global_load_dword v216, v245, s[98:99] offset:-4096
	global_load_dword v217, v245, s[98:99] offset:-2048
	global_load_dword v221, v245, s[98:99]
	global_load_dword v225, v245, s[98:99] offset:2048
	s_add_u32 s98, s8, 0x1f000
	s_addc_u32 s99, s9, 0
	global_load_dword v232, v245, s[98:99] offset:-4096
	global_load_dword v234, v245, s[98:99] offset:-2048
	global_load_dword v238, v245, s[98:99]
	global_load_dword v242, v245, s[98:99] offset:2048
	s_waitcnt vmcnt(0)
	v_fmac_f32_e32 v5, v2, v64
	v_fmac_f32_e32 v140, v2, v48
	v_mul_f32_e32 v13, v140, v140
	v_fmac_f32_e32 v13, v5, v5
	v_fmac_f32_e32 v130, v2, v32
	v_fmac_f32_e32 v13, v130, v130
	v_fmac_f32_e32 v115, v12, v17
	v_fmac_f32_e32 v131, v12, v33
	v_fmac_f32_e32 v142, v12, v49
	v_fmac_f32_e32 v8, v12, v65
	v_mov_b32_e32 v12, v184
	v_fmac_f32_e32 v114, v2, v16
	v_fmac_f32_e32 v13, v114, v114
	v_mul_f32_e32 v11, v142, v142
	v_fmac_f32_e32 v11, v8, v8
	v_fmac_f32_e32 v11, v131, v131
	v_fmac_f32_e32 v11, v115, v115
	v_fmac_f32_e32 v143, v15, v50
	v_mul_f32_e32 v2, v143, v143
	v_fmac_f32_e32 v132, v15, v34
	v_fmac_f32_e32 v9, v15, v66
	v_fmac_f32_e32 v2, v9, v9
	v_fmac_f32_e32 v2, v132, v132
	v_fmac_f32_e32 v116, v15, v18
	v_fmac_f32_e32 v2, v116, v116
	v_fmac_f32_e32 v146, v83, v51
	v_fmac_f32_e32 v10, v83, v67
	v_mul_f32_e32 v81, v146, v146
	v_fmac_f32_e32 v81, v10, v10
	v_fmac_f32_e32 v133, v83, v35
	v_fmac_f32_e32 v81, v133, v133
	v_fmac_f32_e32 v117, v83, v19
	v_fmac_f32_e32 v81, v117, v117
	v_fmac_f32_e32 v155, v14, v52
	v_fmac_f32_e32 v136, v14, v36
	v_fmac_f32_e32 v119, v14, v20
	v_mul_f32_e32 v83, v155, v155
	s_waitcnt vmcnt(0)
	v_fmac_f32_e32 v12, v14, v68
	v_mov_b32_e32 v118, v185
	s_nop 0
	v_mov_b32_e32 v138, v188
	v_mov_b32_e32 v157, v189
	v_mov_b32_e32 v14, v190
	v_add_co_u32_e32 v6, vcc, s85, v0
	v_mov_b32_e32 v120, v191
	v_mov_b32_e32 v139, v192
	v_mov_b32_e32 v158, v193
	v_addc_co_u32_e32 v7, vcc, 0, v1, vcc
	v_add_co_u32_e32 v124, vcc, s4, v0
	s_mov_b32 s4, 0xc000
	s_nop 0
	v_addc_co_u32_e32 v125, vcc, 0, v1, vcc
	v_fmac_f32_e32 v83, v12, v12
	v_fmac_f32_e32 v83, v136, v136
	v_fmac_f32_e32 v83, v119, v119
	s_waitcnt vmcnt(0)
	v_fmac_f32_e32 v118, v80, v21
	v_fmac_f32_e32 v138, v80, v37
	v_fmac_f32_e32 v157, v80, v53
	v_fmac_f32_e32 v14, v80, v69
	v_mov_b32_e32 v80, v194
	v_fmac_f32_e32 v139, v82, v38
	v_fmac_f32_e32 v158, v82, v54
	v_fmac_f32_e32 v120, v82, v22
	v_mul_f32_e32 v15, v157, v157
	v_fmac_f32_e32 v15, v14, v14
	v_fmac_f32_e32 v15, v138, v138
	v_fmac_f32_e32 v15, v118, v118
	v_mul_f32_e32 v85, v158, v158
	s_waitcnt vmcnt(0)
	v_fmac_f32_e32 v80, v82, v70
	v_mov_b32_e32 v121, v195
	s_nop 0
	v_mov_b32_e32 v145, v196
	v_mov_b32_e32 v166, v197
	v_mov_b32_e32 v82, v212
	v_add_co_u32_e32 v6, vcc, s4, v0
	s_movk_i32 s4, 0x6000
	s_nop 0
	v_addc_co_u32_e32 v7, vcc, 0, v1, vcc
	v_add_co_u32_e32 v126, vcc, s90, v0
	v_fmac_f32_e32 v85, v80, v80
	s_nop 0
	v_addc_co_u32_e32 v127, vcc, 0, v1, vcc
	v_add_co_u32_e32 v150, vcc, s86, v0
	v_fmac_f32_e32 v85, v139, v139
	s_nop 0
	v_addc_co_u32_e32 v151, vcc, 0, v1, vcc
	v_add_co_u32_e32 v160, vcc, s89, v0
	v_fmac_f32_e32 v85, v120, v120
	s_nop 0
	v_addc_co_u32_e32 v161, vcc, 0, v1, vcc
	v_add_co_u32_e32 v152, vcc, s87, v0
	v_mov_b32_e32 v170, v213
	v_mov_b32_e32 v149, v214
	v_addc_co_u32_e32 v153, vcc, 0, v1, vcc
	v_add_co_u32_e32 v162, vcc, s88, v0
	s_waitcnt vmcnt(0)
	v_fmac_f32_e32 v121, v84, v23
	v_addc_co_u32_e32 v163, vcc, 0, v1, vcc
	v_fmac_f32_e32 v82, v84, v71
	v_fmac_f32_e32 v166, v84, v55
	v_fmac_f32_e32 v145, v84, v39
	v_mov_b32_e32 v84, v215
	v_mov_b32_e32 v123, v216
	v_add_co_u32_e32 v164, vcc, s91, v0
	v_mul_f32_e32 v89, v166, v166
	s_nop 0
	v_addc_co_u32_e32 v165, vcc, 0, v1, vcc
	v_fmac_f32_e32 v89, v82, v82
	v_fmac_f32_e32 v89, v145, v145
	v_fmac_f32_e32 v89, v121, v121
	v_fmac_f32_e32 v170, v86, v56
	v_fmac_f32_e32 v149, v86, v40
	v_mul_f32_e32 v93, v170, v170
	s_waitcnt vmcnt(0)
	v_fmac_f32_e32 v84, v86, v72
	v_fmac_f32_e32 v123, v86, v24
	v_mov_b32_e32 v122, v217
	s_nop 0
	v_mov_b32_e32 v151, v218
	s_nop 0
	v_mov_b32_e32 v171, v219
	v_mov_b32_e32 v86, v220
	v_add_co_u32_e32 v6, vcc, s4, v0
	v_mov_b32_e32 v124, v221
	v_mov_b32_e32 v152, v222
	v_mov_b32_e32 v172, v223
	v_addc_co_u32_e32 v7, vcc, 0, v1, vcc
	s_mov_b32 s4, 0x1f000
	v_fmac_f32_e32 v93, v84, v84
	v_fmac_f32_e32 v93, v149, v149
	v_fmac_f32_e32 v93, v123, v123
	s_waitcnt vmcnt(0)
	v_fmac_f32_e32 v122, v88, v25
	v_fmac_f32_e32 v151, v88, v41
	v_fmac_f32_e32 v171, v88, v57
	v_fmac_f32_e32 v86, v88, v73
	v_mov_b32_e32 v88, v224
	v_fmac_f32_e32 v152, v90, v42
	v_fmac_f32_e32 v172, v90, v58
	v_fmac_f32_e32 v124, v90, v26
	v_mul_f32_e32 v87, v171, v171
	v_fmac_f32_e32 v87, v86, v86
	v_fmac_f32_e32 v87, v151, v151
	v_fmac_f32_e32 v87, v122, v122
	v_mul_f32_e32 v91, v172, v172
	s_waitcnt vmcnt(0)
	v_fmac_f32_e32 v88, v90, v74
	v_mov_b32_e32 v125, v225
	v_mov_b32_e32 v154, v226
	v_mov_b32_e32 v173, v227
	v_mov_b32_e32 v90, v229
	v_add_co_u32_e32 v160, vcc, s92, v0
	v_fmac_f32_e32 v91, v88, v88
	s_nop 0
	v_addc_co_u32_e32 v161, vcc, 0, v1, vcc
	v_add_co_u32_e32 v162, vcc, s96, v0
	v_fmac_f32_e32 v91, v152, v152
	s_nop 0
	v_addc_co_u32_e32 v163, vcc, 0, v1, vcc
	v_add_co_u32_e32 v168, vcc, s93, v0
	v_fmac_f32_e32 v91, v124, v124
	s_nop 0
	v_addc_co_u32_e32 v169, vcc, 0, v1, vcc
	v_add_co_u32_e32 v178, vcc, s95, v0
	v_mov_b32_e32 v174, v230
	s_nop 0
	v_addc_co_u32_e32 v179, vcc, 0, v1, vcc
	v_add_co_u32_e32 v176, vcc, s94, v0
	v_mov_b32_e32 v164, v231
	s_nop 0
	v_addc_co_u32_e32 v177, vcc, 0, v1, vcc
	v_add_co_u32_e32 v180, vcc, s4, v0
	s_mov_b64 s[4:5], 0x80
	s_nop 0
	v_addc_co_u32_e32 v181, vcc, 0, v1, vcc
	v_mov_b32_e32 v127, v232
	s_waitcnt vmcnt(0)
	v_fmac_f32_e32 v125, v92, v27
	v_fmac_f32_e32 v154, v92, v43
	v_fmac_f32_e32 v173, v92, v59
	v_fmac_f32_e32 v90, v92, v75
	v_mov_b32_e32 v92, v233
	v_mul_f32_e32 v95, v173, v173
	v_fmac_f32_e32 v95, v90, v90
	v_fmac_f32_e32 v95, v154, v154
	v_fmac_f32_e32 v95, v125, v125
	v_fmac_f32_e32 v174, v94, v60
	v_mul_f32_e32 v97, v174, v174
	v_fmac_f32_e32 v164, v94, v44
	v_fmac_f32_e32 v127, v94, v28
	s_waitcnt vmcnt(0)
	v_fmac_f32_e32 v92, v94, v76
	v_mov_b32_e32 v126, v234
	v_mov_b32_e32 v167, v235
	v_mov_b32_e32 v175, v236
	v_mov_b32_e32 v94, v237
	v_add_co_u32_e32 v160, vcc, s97, v0
	v_mov_b32_e32 v128, v238
	v_mov_b32_e32 v168, v239
	v_mov_b32_e32 v176, v240
	v_addc_co_u32_e32 v161, vcc, 0, v1, vcc
	v_fmac_f32_e32 v97, v92, v92
	v_fmac_f32_e32 v97, v164, v164
	v_fmac_f32_e32 v97, v127, v127
	s_waitcnt vmcnt(0)
	v_fmac_f32_e32 v126, v96, v29
	v_fmac_f32_e32 v167, v96, v45
	v_fmac_f32_e32 v175, v96, v61
	v_fmac_f32_e32 v94, v96, v77
	v_mov_b32_e32 v96, v241
	v_fmac_f32_e32 v168, v129, v46
	v_fmac_f32_e32 v176, v129, v62
	v_fmac_f32_e32 v128, v129, v30
	v_mul_f32_e32 v6, v175, v175
	v_fmac_f32_e32 v6, v94, v94
	v_fmac_f32_e32 v6, v167, v167
	v_fmac_f32_e32 v6, v126, v126
	v_mul_f32_e32 v7, v176, v176
	s_waitcnt vmcnt(0)
	v_fmac_f32_e32 v96, v129, v78
	v_mov_b32_e32 v129, v242
	v_mov_b32_e32 v169, v243
	v_mov_b32_e32 v177, v246
	s_nop 0
	v_mov_b32_e32 v178, v247
	v_fmac_f32_e32 v7, v96, v96
	v_fmac_f32_e32 v7, v168, v168
	v_fmac_f32_e32 v7, v128, v128
	s_waitcnt vmcnt(0)
	v_fmac_f32_e32 v129, v134, v31
	v_fmac_f32_e32 v169, v134, v47
	v_fmac_f32_e32 v177, v134, v63
	v_fmac_f32_e32 v178, v134, v79
	s_nop 1
	v_mov_b32_dpp v134, v13 quad_perm:[1,0,3,2] row_mask:0xf bank_mask:0xf
	v_mul_f32_e32 v165, v177, v177
	v_fmac_f32_e32 v165, v178, v178
	v_fmac_f32_e32 v165, v169, v169
	v_fmac_f32_e32 v165, v129, v129
	s_waitcnt lgkmcnt(0)
	v_add_f32_e32 v13, v13, v134
	s_nop 1
	v_mov_b32_dpp v134, v13 quad_perm:[2,3,0,1] row_mask:0xf bank_mask:0xf
	s_waitcnt lgkmcnt(0)
	v_add_f32_e32 v13, v13, v134
	s_nop 1
	v_mov_b32_dpp v134, v13 row_half_mirror row_mask:0xf bank_mask:0xf
	s_waitcnt lgkmcnt(0)
	v_add_f32_e32 v13, v13, v134
	s_nop 1
	v_mov_b32_dpp v134, v13 row_mirror row_mask:0xf bank_mask:0xf
	s_waitcnt lgkmcnt(0)
	v_add_f32_e32 v13, v13, v134
	v_mov_b32_e32 v247, v13
	v_mov_b32_e32 v134, v13
	s_nop 1
	v_permlane16_swap_b32_e32 v247, v134
	v_cndmask_b32_e64 v134, v134, v247, s[100:101]
	s_waitcnt lgkmcnt(0)
	v_add_f32_e32 v13, v13, v134
	v_fmamk_f32 v13, v13, 0x3c000000, v206
	v_rsq_f32_e32 v13, v13
	s_nop 0
	v_mul_f32_e32 v134, 0x3f24fd5c, v13
	s_nop 1
	v_mov_b32_dpp v13, v11 quad_perm:[1,0,3,2] row_mask:0xf bank_mask:0xf
	v_mul_f32_e32 v140, v134, v140
	v_mul_f32_e32 v130, v134, v130
	v_mul_f32_e32 v114, v134, v114
	s_waitcnt lgkmcnt(0)
	v_add_f32_e32 v11, v11, v13
	s_nop 1
	v_mov_b32_dpp v13, v11 quad_perm:[2,3,0,1] row_mask:0xf bank_mask:0xf
	s_waitcnt lgkmcnt(0)
	v_add_f32_e32 v11, v11, v13
	s_nop 1
	v_mov_b32_dpp v13, v11 row_half_mirror row_mask:0xf bank_mask:0xf
	s_waitcnt lgkmcnt(0)
	v_add_f32_e32 v11, v11, v13
	s_nop 1
	v_mov_b32_dpp v13, v11 row_mirror row_mask:0xf bank_mask:0xf
	s_waitcnt lgkmcnt(0)
	v_add_f32_e32 v11, v11, v13
	v_mov_b32_e32 v247, v11
	v_mov_b32_e32 v13, v11
	s_nop 1
	v_permlane16_swap_b32_e32 v247, v13
	v_cndmask_b32_e64 v13, v13, v247, s[100:101]
	s_waitcnt lgkmcnt(0)
	v_add_f32_e32 v11, v11, v13
	v_fmamk_f32 v11, v11, 0x3c000000, v206
	v_rsq_f32_e32 v11, v11
	s_nop 0
	v_mul_f32_e32 v135, 0x3f24fd5c, v11
	s_nop 1
	v_mov_b32_dpp v11, v2 quad_perm:[1,0,3,2] row_mask:0xf bank_mask:0xf
	v_mul_f32_e32 v8, v135, v8
	s_waitcnt lgkmcnt(0)
	v_add_f32_e32 v2, v2, v11
	s_nop 1
	v_mov_b32_dpp v11, v2 quad_perm:[2,3,0,1] row_mask:0xf bank_mask:0xf
	s_waitcnt lgkmcnt(0)
	v_add_f32_e32 v2, v2, v11
	s_nop 1
	v_mov_b32_dpp v11, v2 row_half_mirror row_mask:0xf bank_mask:0xf
	s_waitcnt lgkmcnt(0)
	v_add_f32_e32 v2, v2, v11
	s_nop 1
	v_mov_b32_dpp v11, v2 row_mirror row_mask:0xf bank_mask:0xf
	s_waitcnt lgkmcnt(0)
	v_add_f32_e32 v2, v2, v11
	v_mov_b32_e32 v247, v2
	v_mov_b32_e32 v11, v2
	s_nop 1
	v_permlane16_swap_b32_e32 v247, v11
	v_cndmask_b32_e64 v11, v11, v247, s[100:101]
	s_waitcnt lgkmcnt(0)
	v_add_f32_e32 v2, v2, v11
	v_fmamk_f32 v2, v2, 0x3c000000, v206
	v_rsq_f32_e32 v2, v2
	s_nop 0
	v_mul_f32_e32 v137, 0x3f24fd5c, v2
	s_nop 1
	v_mov_b32_dpp v2, v81 quad_perm:[1,0,3,2] row_mask:0xf bank_mask:0xf
	s_waitcnt lgkmcnt(0)
	v_add_f32_e32 v2, v81, v2
	s_nop 1
	v_mov_b32_dpp v11, v2 quad_perm:[2,3,0,1] row_mask:0xf bank_mask:0xf
	s_waitcnt lgkmcnt(0)
	v_add_f32_e32 v2, v2, v11
	s_nop 1
	v_mov_b32_dpp v11, v2 row_half_mirror row_mask:0xf bank_mask:0xf
	s_waitcnt lgkmcnt(0)
	v_add_f32_e32 v2, v2, v11
	s_nop 1
	v_mov_b32_dpp v11, v2 row_mirror row_mask:0xf bank_mask:0xf
	s_waitcnt lgkmcnt(0)
	v_add_f32_e32 v2, v2, v11
	v_mov_b32_e32 v247, v2
	v_mov_b32_e32 v11, v2
	s_nop 1
	v_permlane16_swap_b32_e32 v247, v11
	v_cndmask_b32_e64 v11, v11, v247, s[100:101]
	s_waitcnt lgkmcnt(0)
	v_add_f32_e32 v2, v2, v11
	v_fmamk_f32 v2, v2, 0x3c000000, v206
	v_rsq_f32_e32 v2, v2
	s_nop 0
	v_mul_f32_e32 v141, 0x3f24fd5c, v2
	s_nop 1
	v_mov_b32_dpp v2, v83 quad_perm:[1,0,3,2] row_mask:0xf bank_mask:0xf
	v_mul_f32_e32 v10, v141, v10
	s_waitcnt lgkmcnt(0)
	v_add_f32_e32 v2, v83, v2
	s_nop 1
	v_mov_b32_dpp v11, v2 quad_perm:[2,3,0,1] row_mask:0xf bank_mask:0xf
	s_waitcnt lgkmcnt(0)
	v_add_f32_e32 v2, v2, v11
	s_nop 1
	v_mov_b32_dpp v11, v2 row_half_mirror row_mask:0xf bank_mask:0xf
	s_waitcnt lgkmcnt(0)
	v_add_f32_e32 v2, v2, v11
	s_nop 1
	v_mov_b32_dpp v11, v2 row_mirror row_mask:0xf bank_mask:0xf
	s_waitcnt lgkmcnt(0)
	v_add_f32_e32 v2, v2, v11
	v_mov_b32_e32 v247, v2
	v_mov_b32_e32 v11, v2
	s_nop 1
	v_permlane16_swap_b32_e32 v247, v11
	v_cndmask_b32_e64 v11, v11, v247, s[100:101]
	s_waitcnt lgkmcnt(0)
	v_add_f32_e32 v2, v2, v11
	v_fmamk_f32 v2, v2, 0x3c000000, v206
	v_rsq_f32_e32 v2, v2
	s_nop 0
	v_mul_f32_e32 v144, 0x3f24fd5c, v2
	s_nop 1
	v_mov_b32_dpp v2, v15 quad_perm:[1,0,3,2] row_mask:0xf bank_mask:0xf
	v_mul_f32_e32 v12, v144, v12
	s_waitcnt lgkmcnt(0)
	v_add_f32_e32 v2, v15, v2
	s_nop 1
	v_mov_b32_dpp v11, v2 quad_perm:[2,3,0,1] row_mask:0xf bank_mask:0xf
	s_waitcnt lgkmcnt(0)
	v_add_f32_e32 v2, v2, v11
	s_nop 1
	v_mov_b32_dpp v11, v2 row_half_mirror row_mask:0xf bank_mask:0xf
	s_waitcnt lgkmcnt(0)
	v_add_f32_e32 v2, v2, v11
	s_nop 1
	v_mov_b32_dpp v11, v2 row_mirror row_mask:0xf bank_mask:0xf
	s_waitcnt lgkmcnt(0)
	v_add_f32_e32 v2, v2, v11
	v_mov_b32_e32 v247, v2
	v_mov_b32_e32 v11, v2
	s_nop 1
	v_permlane16_swap_b32_e32 v247, v11
	v_cndmask_b32_e64 v11, v11, v247, s[100:101]
	s_waitcnt lgkmcnt(0)
	v_add_f32_e32 v2, v2, v11
	v_fmamk_f32 v2, v2, 0x3c000000, v206
	v_rsq_f32_e32 v2, v2
	s_nop 0
	v_mul_f32_e32 v147, 0x3f24fd5c, v2
	s_nop 1
	v_mov_b32_dpp v2, v85 quad_perm:[1,0,3,2] row_mask:0xf bank_mask:0xf
	v_mul_f32_e32 v14, v147, v14
	s_waitcnt lgkmcnt(0)
	v_add_f32_e32 v2, v85, v2
	s_nop 1
	v_mov_b32_dpp v11, v2 quad_perm:[2,3,0,1] row_mask:0xf bank_mask:0xf
	s_waitcnt lgkmcnt(0)
	v_add_f32_e32 v2, v2, v11
	s_nop 1
	v_mov_b32_dpp v11, v2 row_half_mirror row_mask:0xf bank_mask:0xf
	s_waitcnt lgkmcnt(0)
	v_add_f32_e32 v2, v2, v11
	s_nop 1
	v_mov_b32_dpp v11, v2 row_mirror row_mask:0xf bank_mask:0xf
	s_waitcnt lgkmcnt(0)
	v_add_f32_e32 v2, v2, v11
	v_mov_b32_e32 v247, v2
	v_mov_b32_e32 v11, v2
	s_nop 1
	v_permlane16_swap_b32_e32 v247, v11
	v_cndmask_b32_e64 v11, v11, v247, s[100:101]
	s_waitcnt lgkmcnt(0)
	v_add_f32_e32 v2, v2, v11
	v_fmamk_f32 v2, v2, 0x3c000000, v206
	v_rsq_f32_e32 v2, v2
	s_nop 0
	v_mul_f32_e32 v148, 0x3f24fd5c, v2
	s_nop 1
	v_mov_b32_dpp v2, v89 quad_perm:[1,0,3,2] row_mask:0xf bank_mask:0xf
	v_mul_f32_e32 v80, v148, v80
	s_waitcnt lgkmcnt(0)
	v_add_f32_e32 v2, v89, v2
	s_nop 1
	v_mov_b32_dpp v11, v2 quad_perm:[2,3,0,1] row_mask:0xf bank_mask:0xf
	s_waitcnt lgkmcnt(0)
	v_add_f32_e32 v2, v2, v11
	s_nop 1
	v_mov_b32_dpp v11, v2 row_half_mirror row_mask:0xf bank_mask:0xf
	s_waitcnt lgkmcnt(0)
	v_add_f32_e32 v2, v2, v11
	s_nop 1
	v_mov_b32_dpp v11, v2 row_mirror row_mask:0xf bank_mask:0xf
	s_waitcnt lgkmcnt(0)
	v_add_f32_e32 v2, v2, v11
	v_mov_b32_e32 v247, v2
	v_mov_b32_e32 v11, v2
	s_nop 1
	v_permlane16_swap_b32_e32 v247, v11
	v_cndmask_b32_e64 v11, v11, v247, s[100:101]
	s_waitcnt lgkmcnt(0)
	v_add_f32_e32 v2, v2, v11
	v_fmamk_f32 v2, v2, 0x3c000000, v206
	v_rsq_f32_e32 v2, v2
	s_nop 0
	v_mul_f32_e32 v150, 0x3f24fd5c, v2
	s_nop 1
	v_mov_b32_dpp v2, v93 quad_perm:[1,0,3,2] row_mask:0xf bank_mask:0xf
	v_mul_f32_e32 v82, v150, v82
	s_waitcnt lgkmcnt(0)
	v_add_f32_e32 v2, v93, v2
	s_nop 1
	v_mov_b32_dpp v11, v2 quad_perm:[2,3,0,1] row_mask:0xf bank_mask:0xf
	s_waitcnt lgkmcnt(0)
	v_add_f32_e32 v2, v2, v11
	s_nop 1
	v_mov_b32_dpp v11, v2 row_half_mirror row_mask:0xf bank_mask:0xf
	s_waitcnt lgkmcnt(0)
	v_add_f32_e32 v2, v2, v11
	s_nop 1
	v_mov_b32_dpp v11, v2 row_mirror row_mask:0xf bank_mask:0xf
	s_waitcnt lgkmcnt(0)
	v_add_f32_e32 v2, v2, v11
	v_mov_b32_e32 v247, v2
	v_mov_b32_e32 v11, v2
	s_nop 1
	v_permlane16_swap_b32_e32 v247, v11
	v_cndmask_b32_e64 v11, v11, v247, s[100:101]
	s_waitcnt lgkmcnt(0)
	v_add_f32_e32 v2, v2, v11
	v_fmamk_f32 v2, v2, 0x3c000000, v206
	v_rsq_f32_e32 v2, v2
	s_nop 0
	v_mul_f32_e32 v153, 0x3f24fd5c, v2
	s_nop 1
	v_mov_b32_dpp v2, v87 quad_perm:[1,0,3,2] row_mask:0xf bank_mask:0xf
	v_mul_f32_e32 v84, v153, v84
	s_waitcnt lgkmcnt(0)
	v_add_f32_e32 v2, v87, v2
	s_nop 1
	v_mov_b32_dpp v11, v2 quad_perm:[2,3,0,1] row_mask:0xf bank_mask:0xf
	s_waitcnt lgkmcnt(0)
	v_add_f32_e32 v2, v2, v11
	s_nop 1
	v_mov_b32_dpp v11, v2 row_half_mirror row_mask:0xf bank_mask:0xf
	s_waitcnt lgkmcnt(0)
	v_add_f32_e32 v2, v2, v11
	s_nop 1
	v_mov_b32_dpp v11, v2 row_mirror row_mask:0xf bank_mask:0xf
	s_waitcnt lgkmcnt(0)
	v_add_f32_e32 v2, v2, v11
	v_mov_b32_e32 v247, v2
	v_mov_b32_e32 v11, v2
	s_nop 1
	v_permlane16_swap_b32_e32 v247, v11
	v_cndmask_b32_e64 v11, v11, v247, s[100:101]
	s_waitcnt lgkmcnt(0)
	v_add_f32_e32 v2, v2, v11
	v_fmamk_f32 v2, v2, 0x3c000000, v206
	v_rsq_f32_e32 v2, v2
	s_nop 0
	v_mul_f32_e32 v156, 0x3f24fd5c, v2
	s_nop 1
	v_mov_b32_dpp v2, v91 quad_perm:[1,0,3,2] row_mask:0xf bank_mask:0xf
	v_mul_f32_e32 v86, v156, v86
	s_waitcnt lgkmcnt(0)
	v_add_f32_e32 v2, v91, v2
	s_nop 1
	v_mov_b32_dpp v11, v2 quad_perm:[2,3,0,1] row_mask:0xf bank_mask:0xf
	s_waitcnt lgkmcnt(0)
	v_add_f32_e32 v2, v2, v11
	s_nop 1
	v_mov_b32_dpp v11, v2 row_half_mirror row_mask:0xf bank_mask:0xf
	s_waitcnt lgkmcnt(0)
	v_add_f32_e32 v2, v2, v11
	s_nop 1
	v_mov_b32_dpp v11, v2 row_mirror row_mask:0xf bank_mask:0xf
	s_waitcnt lgkmcnt(0)
	v_add_f32_e32 v2, v2, v11
	v_mov_b32_e32 v247, v2
	v_mov_b32_e32 v11, v2
	s_nop 1
	v_permlane16_swap_b32_e32 v247, v11
	v_cndmask_b32_e64 v11, v11, v247, s[100:101]
	s_waitcnt lgkmcnt(0)
	v_add_f32_e32 v2, v2, v11
	v_fmamk_f32 v2, v2, 0x3c000000, v206
	v_rsq_f32_e32 v2, v2
	s_nop 0
	v_mul_f32_e32 v159, 0x3f24fd5c, v2
	s_nop 1
	v_mov_b32_dpp v2, v95 quad_perm:[1,0,3,2] row_mask:0xf bank_mask:0xf
	v_mul_f32_e32 v88, v159, v88
	s_waitcnt lgkmcnt(0)
	v_add_f32_e32 v2, v95, v2
	s_nop 1
	v_mov_b32_dpp v11, v2 quad_perm:[2,3,0,1] row_mask:0xf bank_mask:0xf
	s_waitcnt lgkmcnt(0)
	v_add_f32_e32 v2, v2, v11
	s_nop 1
	v_mov_b32_dpp v11, v2 row_half_mirror row_mask:0xf bank_mask:0xf
	s_waitcnt lgkmcnt(0)
	v_add_f32_e32 v2, v2, v11
	s_nop 1
	v_mov_b32_dpp v11, v2 row_mirror row_mask:0xf bank_mask:0xf
	s_waitcnt lgkmcnt(0)
	v_add_f32_e32 v2, v2, v11
	v_mov_b32_e32 v247, v2
	v_mov_b32_e32 v11, v2
	s_nop 1
	v_permlane16_swap_b32_e32 v247, v11
	v_cndmask_b32_e64 v11, v11, v247, s[100:101]
	s_waitcnt lgkmcnt(0)
	v_add_f32_e32 v2, v2, v11
	v_fmamk_f32 v2, v2, 0x3c000000, v206
	v_rsq_f32_e32 v2, v2
	s_nop 0
	v_mul_f32_e32 v160, 0x3f24fd5c, v2
	s_nop 1
	v_mov_b32_dpp v2, v97 quad_perm:[1,0,3,2] row_mask:0xf bank_mask:0xf
	v_mul_f32_e32 v90, v160, v90
	s_waitcnt lgkmcnt(0)
	v_add_f32_e32 v2, v97, v2
	s_nop 1
	v_mov_b32_dpp v11, v2 quad_perm:[2,3,0,1] row_mask:0xf bank_mask:0xf
	s_waitcnt lgkmcnt(0)
	v_add_f32_e32 v2, v2, v11
	s_nop 1
	v_mov_b32_dpp v11, v2 row_half_mirror row_mask:0xf bank_mask:0xf
	s_waitcnt lgkmcnt(0)
	v_add_f32_e32 v2, v2, v11
	s_nop 1
	v_mov_b32_dpp v11, v2 row_mirror row_mask:0xf bank_mask:0xf
	s_waitcnt lgkmcnt(0)
	v_add_f32_e32 v2, v2, v11
	v_mov_b32_e32 v247, v2
	v_mov_b32_e32 v11, v2
	s_nop 1
	v_permlane16_swap_b32_e32 v247, v11
	v_cndmask_b32_e64 v11, v11, v247, s[100:101]
	s_waitcnt lgkmcnt(0)
	v_add_f32_e32 v2, v2, v11
	v_fmamk_f32 v2, v2, 0x3c000000, v206
	v_rsq_f32_e32 v2, v2
	v_and_b32_e32 v11, 31, v4
	v_lshlrev_b32_e32 v179, 2, v11
	global_load_dword v182, v179, s[6:7]
	v_mul_f32_e32 v161, 0x3f24fd5c, v2
	s_nop 1
	v_mov_b32_dpp v2, v6 quad_perm:[1,0,3,2] row_mask:0xf bank_mask:0xf
	v_mul_f32_e32 v92, v161, v92
	s_waitcnt lgkmcnt(0)
	v_add_f32_e32 v2, v6, v2
	s_nop 1
	v_mov_b32_dpp v6, v2 quad_perm:[2,3,0,1] row_mask:0xf bank_mask:0xf
	s_waitcnt lgkmcnt(0)
	v_add_f32_e32 v2, v2, v6
	s_nop 1
	v_mov_b32_dpp v6, v2 row_half_mirror row_mask:0xf bank_mask:0xf
	s_waitcnt lgkmcnt(0)
	v_add_f32_e32 v2, v2, v6
	s_nop 1
	v_mov_b32_dpp v6, v2 row_mirror row_mask:0xf bank_mask:0xf
	s_waitcnt lgkmcnt(0)
	v_add_f32_e32 v2, v2, v6
	v_mov_b32_e32 v247, v2
	v_mov_b32_e32 v6, v2
	s_nop 1
	v_permlane16_swap_b32_e32 v247, v6
	v_cndmask_b32_e64 v6, v6, v247, s[100:101]
	s_waitcnt lgkmcnt(0)
	v_add_f32_e32 v2, v2, v6
	v_fmamk_f32 v2, v2, 0x3c000000, v206
	v_rsq_f32_e32 v2, v2
	s_waitcnt vmcnt(0)
	v_mul_f32_e32 v8, v182, v8
	v_mul_f32_e32 v162, 0x3f24fd5c, v2
	s_nop 1
	v_mov_b32_dpp v2, v7 quad_perm:[1,0,3,2] row_mask:0xf bank_mask:0xf
	v_mul_f32_e32 v10, v182, v10
	v_mul_f32_e32 v12, v182, v12
	v_mul_f32_e32 v14, v182, v14
	v_mul_f32_e32 v80, v182, v80
	s_waitcnt lgkmcnt(0)
	v_add_f32_e32 v2, v7, v2
	s_nop 1
	v_mov_b32_dpp v6, v2 quad_perm:[2,3,0,1] row_mask:0xf bank_mask:0xf
	v_mul_f32_e32 v82, v182, v82
	v_mul_f32_e32 v84, v182, v84
	v_mul_f32_e32 v86, v182, v86
	v_mul_f32_e32 v88, v182, v88
	s_waitcnt lgkmcnt(0)
	v_add_f32_e32 v2, v2, v6
	s_nop 1
	v_mov_b32_dpp v6, v2 row_half_mirror row_mask:0xf bank_mask:0xf
	v_mul_f32_e32 v90, v182, v90
	v_mul_f32_e32 v92, v182, v92
	v_mul_f32_e32 v94, v162, v94
	v_mul_f32_e32 v94, v182, v94
	s_waitcnt lgkmcnt(0)
	v_add_f32_e32 v2, v2, v6
	s_nop 1
	v_mov_b32_dpp v6, v2 row_mirror row_mask:0xf bank_mask:0xf
	s_waitcnt lgkmcnt(0)
	v_add_f32_e32 v2, v2, v6
	v_mov_b32_e32 v247, v2
	v_mov_b32_e32 v6, v2
	s_nop 1
	v_permlane16_swap_b32_e32 v247, v6
	v_cndmask_b32_e64 v6, v6, v247, s[100:101]
	s_waitcnt lgkmcnt(0)
	v_add_f32_e32 v2, v2, v6
	v_fmamk_f32 v2, v2, 0x3c000000, v206
	v_rsq_f32_e32 v2, v2
	s_nop 0
	v_mul_f32_e32 v163, 0x3f24fd5c, v2
	s_nop 1
	v_mov_b32_dpp v2, v165 quad_perm:[1,0,3,2] row_mask:0xf bank_mask:0xf
	v_mul_f32_e32 v96, v163, v96
	v_mul_f32_e32 v96, v182, v96
	s_waitcnt lgkmcnt(0)
	v_add_f32_e32 v2, v165, v2
	s_nop 1
	v_mov_b32_dpp v6, v2 quad_perm:[2,3,0,1] row_mask:0xf bank_mask:0xf
	s_waitcnt lgkmcnt(0)
	v_add_f32_e32 v2, v2, v6
	s_nop 1
	v_mov_b32_dpp v6, v2 row_half_mirror row_mask:0xf bank_mask:0xf
	s_waitcnt lgkmcnt(0)
	v_add_f32_e32 v2, v2, v6
	s_nop 1
	v_mov_b32_dpp v6, v2 row_mirror row_mask:0xf bank_mask:0xf
	s_waitcnt lgkmcnt(0)
	v_add_f32_e32 v2, v2, v6
	v_mov_b32_e32 v247, v2
	v_mov_b32_e32 v6, v2
	s_nop 1
	v_permlane16_swap_b32_e32 v247, v6
	v_cndmask_b32_e64 v6, v6, v247, s[100:101]
	s_waitcnt lgkmcnt(0)
	v_add_f32_e32 v2, v2, v6
	v_fmamk_f32 v2, v2, 0x3c000000, v206
	v_rsq_f32_e32 v2, v2
	s_nop 0
	v_mul_f32_e32 v165, 0x3f24fd5c, v2
	v_lshlrev_b32_e32 v2, 1, v11
	v_lshl_add_u64 v[6:7], s[46:47], 0, v[2:3]
	v_mul_f32_e32 v2, v134, v5
	v_mul_f32_e32 v2, v182, v2
	v_bfe_u32 v5, v2, 16, 1
	v_add3_u32 v11, v2, v5, s30
	v_lshlrev_b32_e32 v2, 8, v4
	v_and_b32_e32 v2, 0x2000, v2
	v_lshl_add_u64 v[4:5], v[6:7], 0, v[2:3]
	global_store_short_d16_hi v[4:5], v11, off
	v_bfe_u32 v11, v8, 16, 1
	v_add3_u32 v8, v8, v11, s30
	global_store_short_d16_hi v[4:5], v8, off offset:2048
	v_mul_f32_e32 v8, v137, v9
	v_mul_f32_e32 v8, v182, v8
	v_bfe_u32 v9, v8, 16, 1
	v_add3_u32 v11, v8, v9, s30
	v_or_b32_e32 v8, 0x1000, v2
	v_mov_b32_e32 v9, v3
	v_lshl_add_u64 v[180:181], v[6:7], 0, v[8:9]
	global_store_short_d16_hi v[180:181], v11, off
	v_bfe_u32 v11, v10, 16, 1
	v_add3_u32 v13, v10, v11, s30
	v_or_b32_e32 v10, 0x1800, v2
	v_mov_b32_e32 v11, v3
	v_lshl_add_u64 v[180:181], v[6:7], 0, v[10:11]
	global_store_short_d16_hi v[180:181], v13, off
	v_bfe_u32 v13, v12, 16, 1
	v_add3_u32 v15, v12, v13, s30
	v_or_b32_e32 v12, 0x4000, v2
	v_mov_b32_e32 v13, v3
	v_lshl_add_u64 v[180:181], v[6:7], 0, v[12:13]
	global_store_short_d16_hi v[180:181], v15, off
	v_bfe_u32 v15, v14, 16, 1
	v_add3_u32 v81, v14, v15, s30
	v_or_b32_e32 v14, 0x4800, v2
	v_mov_b32_e32 v15, v3
	v_lshl_add_u64 v[180:181], v[6:7], 0, v[14:15]
	global_store_short_d16_hi v[180:181], v81, off
	v_bfe_u32 v81, v80, 16, 1
	v_add3_u32 v83, v80, v81, s30
	v_or_b32_e32 v80, 0x5000, v2
	v_mov_b32_e32 v81, v3
	v_lshl_add_u64 v[180:181], v[6:7], 0, v[80:81]
	global_store_short_d16_hi v[180:181], v83, off
	v_bfe_u32 v83, v82, 16, 1
	v_add3_u32 v85, v82, v83, s30
	v_or_b32_e32 v82, 0x5800, v2
	v_mov_b32_e32 v83, v3
	v_lshl_add_u64 v[180:181], v[6:7], 0, v[82:83]
	global_store_short_d16_hi v[180:181], v85, off
	v_bfe_u32 v85, v84, 16, 1
	v_add3_u32 v87, v84, v85, s30
	v_or_b32_e32 v84, 0x8000, v2
	v_mov_b32_e32 v85, v3
	v_lshl_add_u64 v[180:181], v[6:7], 0, v[84:85]
	global_store_short_d16_hi v[180:181], v87, off
	v_bfe_u32 v87, v86, 16, 1
	v_add3_u32 v89, v86, v87, s30
	v_or_b32_e32 v86, 0x8800, v2
	v_mov_b32_e32 v87, v3
	v_lshl_add_u64 v[180:181], v[6:7], 0, v[86:87]
	global_store_short_d16_hi v[180:181], v89, off
	v_bfe_u32 v89, v88, 16, 1
	v_add3_u32 v91, v88, v89, s30
	v_or_b32_e32 v88, 0x9000, v2
	v_mov_b32_e32 v89, v3
	v_lshl_add_u64 v[180:181], v[6:7], 0, v[88:89]
	global_store_short_d16_hi v[180:181], v91, off
	v_bfe_u32 v91, v90, 16, 1
	v_add3_u32 v93, v90, v91, s30
	v_or_b32_e32 v90, 0x9800, v2
	v_mov_b32_e32 v91, v3
	v_lshl_add_u64 v[180:181], v[6:7], 0, v[90:91]
	global_store_short_d16_hi v[180:181], v93, off
	v_bfe_u32 v93, v92, 16, 1
	v_add3_u32 v95, v92, v93, s30
	v_or_b32_e32 v92, 0xc000, v2
	v_mov_b32_e32 v93, v3
	v_lshl_add_u64 v[180:181], v[6:7], 0, v[92:93]
	global_store_short_d16_hi v[180:181], v95, off
	v_bfe_u32 v95, v94, 16, 1
	v_add3_u32 v97, v94, v95, s30
	v_or_b32_e32 v94, 0xc800, v2
	v_mov_b32_e32 v95, v3
	v_lshl_add_u64 v[180:181], v[6:7], 0, v[94:95]
	global_store_short_d16_hi v[180:181], v97, off
	v_bfe_u32 v97, v96, 16, 1
	v_add3_u32 v183, v96, v97, s30
	v_or_b32_e32 v96, 0xd000, v2
	v_mov_b32_e32 v97, v3
	v_mul_f32_e32 v178, v165, v178
	v_lshl_add_u64 v[180:181], v[6:7], 0, v[96:97]
	v_mul_f32_e32 v178, v182, v178
	global_store_short_d16_hi v[180:181], v183, off
	v_bfe_u32 v180, v178, 16, 1
	v_or_b32_e32 v2, 0xd800, v2
	v_add3_u32 v178, v178, v180, s30
	v_lshl_add_u64 v[180:181], v[6:7], 0, v[2:3]
	global_store_short_d16_hi v[180:181], v178, off
	global_load_dword v178, v179, s[6:7] offset:128
	v_lshl_add_u64 v[180:181], v[6:7], 0, 64
	s_waitcnt vmcnt(0)
	v_mul_f32_e32 v140, v178, v140
	v_bfe_u32 v182, v140, 16, 1
	v_add3_u32 v140, v140, v182, s30
	global_store_short_d16_hi v[4:5], v140, off offset:64
	v_mul_f32_e32 v140, v135, v142
	v_mul_f32_e32 v140, v178, v140
	v_bfe_u32 v142, v140, 16, 1
	v_add3_u32 v140, v140, v142, s30
	global_store_short_d16_hi v[4:5], v140, off offset:2112
	v_mul_f32_e32 v140, v137, v143
	v_mul_f32_e32 v140, v178, v140
	v_bfe_u32 v142, v140, 16, 1
	v_add3_u32 v140, v140, v142, s30
	v_lshl_add_u64 v[142:143], v[180:181], 0, v[8:9]
	global_store_short_d16_hi v[142:143], v140, off
	v_mul_f32_e32 v140, v141, v146
	v_mul_f32_e32 v140, v178, v140
	v_bfe_u32 v142, v140, 16, 1
	v_add3_u32 v140, v140, v142, s30
	v_lshl_add_u64 v[142:143], v[180:181], 0, v[10:11]
	global_store_short_d16_hi v[142:143], v140, off
	v_mul_f32_e32 v140, v144, v155
	v_mul_f32_e32 v140, v178, v140
	v_bfe_u32 v142, v140, 16, 1
	v_add3_u32 v140, v140, v142, s30
	v_lshl_add_u64 v[142:143], v[180:181], 0, v[12:13]
	global_store_short_d16_hi v[142:143], v140, off
	v_mul_f32_e32 v140, v147, v157
	v_mul_f32_e32 v140, v178, v140
	v_bfe_u32 v142, v140, 16, 1
	v_add3_u32 v140, v140, v142, s30
	v_lshl_add_u64 v[142:143], v[180:181], 0, v[14:15]
	global_store_short_d16_hi v[142:143], v140, off
	v_mul_f32_e32 v140, v148, v158
	v_mul_f32_e32 v140, v178, v140
	v_bfe_u32 v142, v140, 16, 1
	v_add3_u32 v140, v140, v142, s30
	v_lshl_add_u64 v[142:143], v[180:181], 0, v[80:81]
	global_store_short_d16_hi v[142:143], v140, off
	v_mul_f32_e32 v140, v150, v166
	v_mul_f32_e32 v140, v178, v140
	v_bfe_u32 v142, v140, 16, 1
	v_add3_u32 v140, v140, v142, s30
	v_lshl_add_u64 v[142:143], v[180:181], 0, v[82:83]
	global_store_short_d16_hi v[142:143], v140, off
	v_mul_f32_e32 v140, v153, v170
	v_mul_f32_e32 v140, v178, v140
	v_bfe_u32 v142, v140, 16, 1
	v_add3_u32 v140, v140, v142, s30
	v_lshl_add_u64 v[142:143], v[180:181], 0, v[84:85]
	global_store_short_d16_hi v[142:143], v140, off
	v_mul_f32_e32 v140, v156, v171
	v_mul_f32_e32 v140, v178, v140
	v_bfe_u32 v142, v140, 16, 1
	v_add3_u32 v140, v140, v142, s30
	v_lshl_add_u64 v[142:143], v[180:181], 0, v[86:87]
	global_store_short_d16_hi v[142:143], v140, off
	v_mul_f32_e32 v140, v159, v172
	v_mul_f32_e32 v140, v178, v140
	v_bfe_u32 v142, v140, 16, 1
	v_add3_u32 v140, v140, v142, s30
	v_lshl_add_u64 v[142:143], v[180:181], 0, v[88:89]
	global_store_short_d16_hi v[142:143], v140, off
	v_mul_f32_e32 v140, v160, v173
	v_mul_f32_e32 v140, v178, v140
	v_bfe_u32 v142, v140, 16, 1
	v_add3_u32 v140, v140, v142, s30
	v_lshl_add_u64 v[142:143], v[180:181], 0, v[90:91]
	global_store_short_d16_hi v[142:143], v140, off
	v_mul_f32_e32 v140, v161, v174
	v_mul_f32_e32 v140, v178, v140
	v_bfe_u32 v142, v140, 16, 1
	v_add3_u32 v140, v140, v142, s30
	v_lshl_add_u64 v[142:143], v[180:181], 0, v[92:93]
	global_store_short_d16_hi v[142:143], v140, off
	v_mul_f32_e32 v140, v162, v175
	v_mul_f32_e32 v140, v178, v140
	v_bfe_u32 v142, v140, 16, 1
	v_add3_u32 v140, v140, v142, s30
	v_lshl_add_u64 v[142:143], v[180:181], 0, v[94:95]
	global_store_short_d16_hi v[142:143], v140, off
	v_mul_f32_e32 v140, v163, v176
	v_mul_f32_e32 v140, v178, v140
	v_bfe_u32 v142, v140, 16, 1
	v_add3_u32 v140, v140, v142, s30
	v_lshl_add_u64 v[142:143], v[180:181], 0, v[96:97]
	global_store_short_d16_hi v[142:143], v140, off
	v_mul_f32_e32 v140, v165, v177
	v_mul_f32_e32 v140, v178, v140
	v_bfe_u32 v142, v140, 16, 1
	v_add3_u32 v140, v140, v142, s30
	v_lshl_add_u64 v[142:143], v[180:181], 0, v[2:3]
	global_store_short_d16_hi v[142:143], v140, off
	global_load_dword v140, v179, s[6:7] offset:256
	v_lshl_add_u64 v[142:143], v[6:7], 0, s[4:5]
	s_mov_b64 s[4:5], 0xc0
	v_lshl_add_u64 v[6:7], v[6:7], 0, s[4:5]
	s_mov_b64 s[4:5], 0
	s_waitcnt vmcnt(0)
	v_mul_f32_e32 v130, v140, v130
	v_bfe_u32 v146, v130, 16, 1
	v_add3_u32 v130, v130, v146, s30
	global_store_short_d16_hi v[4:5], v130, off offset:128
	v_mul_f32_e32 v130, v135, v131
	v_mul_f32_e32 v130, v140, v130
	v_bfe_u32 v131, v130, 16, 1
	v_add3_u32 v130, v130, v131, s30
	global_store_short_d16_hi v[4:5], v130, off offset:2176
	v_mul_f32_e32 v130, v137, v132
	v_mul_f32_e32 v130, v140, v130
	v_bfe_u32 v131, v130, 16, 1
	v_add3_u32 v132, v130, v131, s30
	v_lshl_add_u64 v[130:131], v[142:143], 0, v[8:9]
	global_store_short_d16_hi v[130:131], v132, off
	v_mul_f32_e32 v130, v141, v133
	v_mul_f32_e32 v130, v140, v130
	v_bfe_u32 v131, v130, 16, 1
	v_add3_u32 v132, v130, v131, s30
	v_lshl_add_u64 v[130:131], v[142:143], 0, v[10:11]
	global_store_short_d16_hi v[130:131], v132, off
	v_mul_f32_e32 v130, v144, v136
	v_mul_f32_e32 v130, v140, v130
	v_bfe_u32 v131, v130, 16, 1
	v_add3_u32 v132, v130, v131, s30
	v_lshl_add_u64 v[130:131], v[142:143], 0, v[12:13]
	global_store_short_d16_hi v[130:131], v132, off
	v_mul_f32_e32 v130, v147, v138
	v_mul_f32_e32 v130, v140, v130
	v_bfe_u32 v131, v130, 16, 1
	v_add3_u32 v132, v130, v131, s30
	v_lshl_add_u64 v[130:131], v[142:143], 0, v[14:15]
	global_store_short_d16_hi v[130:131], v132, off
	v_mul_f32_e32 v130, v148, v139
	v_mul_f32_e32 v130, v140, v130
	v_bfe_u32 v131, v130, 16, 1
	v_add3_u32 v132, v130, v131, s30
	v_lshl_add_u64 v[130:131], v[142:143], 0, v[80:81]
	global_store_short_d16_hi v[130:131], v132, off
	v_mul_f32_e32 v130, v150, v145
	v_mul_f32_e32 v130, v140, v130
	v_bfe_u32 v131, v130, 16, 1
	v_add3_u32 v132, v130, v131, s30
	v_lshl_add_u64 v[130:131], v[142:143], 0, v[82:83]
	global_store_short_d16_hi v[130:131], v132, off
	v_mul_f32_e32 v130, v153, v149
	v_mul_f32_e32 v130, v140, v130
	v_bfe_u32 v131, v130, 16, 1
	v_add3_u32 v132, v130, v131, s30
	v_lshl_add_u64 v[130:131], v[142:143], 0, v[84:85]
	global_store_short_d16_hi v[130:131], v132, off
	v_mul_f32_e32 v130, v156, v151
	v_mul_f32_e32 v130, v140, v130
	v_bfe_u32 v131, v130, 16, 1
	v_add3_u32 v132, v130, v131, s30
	v_lshl_add_u64 v[130:131], v[142:143], 0, v[86:87]
	global_store_short_d16_hi v[130:131], v132, off
	v_mul_f32_e32 v130, v159, v152
	v_mul_f32_e32 v130, v140, v130
	v_bfe_u32 v131, v130, 16, 1
	v_add3_u32 v132, v130, v131, s30
	v_lshl_add_u64 v[130:131], v[142:143], 0, v[88:89]
	global_store_short_d16_hi v[130:131], v132, off
	v_mul_f32_e32 v130, v160, v154
	v_mul_f32_e32 v130, v140, v130
	v_bfe_u32 v131, v130, 16, 1
	v_add3_u32 v132, v130, v131, s30
	v_lshl_add_u64 v[130:131], v[142:143], 0, v[90:91]
	global_store_short_d16_hi v[130:131], v132, off
	v_mul_f32_e32 v130, v161, v164
	v_mul_f32_e32 v130, v140, v130
	v_bfe_u32 v131, v130, 16, 1
	v_add3_u32 v132, v130, v131, s30
	v_lshl_add_u64 v[130:131], v[142:143], 0, v[92:93]
	global_store_short_d16_hi v[130:131], v132, off
	v_mul_f32_e32 v130, v162, v167
	v_mul_f32_e32 v130, v140, v130
	v_bfe_u32 v131, v130, 16, 1
	v_add3_u32 v132, v130, v131, s30
	v_lshl_add_u64 v[130:131], v[142:143], 0, v[94:95]
	global_store_short_d16_hi v[130:131], v132, off
	v_mul_f32_e32 v130, v163, v168
	v_mul_f32_e32 v130, v140, v130
	v_bfe_u32 v131, v130, 16, 1
	v_add3_u32 v132, v130, v131, s30
	v_lshl_add_u64 v[130:131], v[142:143], 0, v[96:97]
	global_store_short_d16_hi v[130:131], v132, off
	v_mul_f32_e32 v130, v165, v169
	v_mul_f32_e32 v130, v140, v130
	v_bfe_u32 v131, v130, 16, 1
	v_add3_u32 v132, v130, v131, s30
	v_lshl_add_u64 v[130:131], v[142:143], 0, v[2:3]
	global_store_short_d16_hi v[130:131], v132, off
	global_load_dword v130, v179, s[6:7] offset:384
	s_waitcnt vmcnt(0)
	v_mul_f32_e32 v114, v130, v114
	v_bfe_u32 v131, v114, 16, 1
	v_add3_u32 v114, v114, v131, s30
	global_store_short_d16_hi v[4:5], v114, off offset:192
	v_mul_f32_e32 v114, v135, v115
	v_mul_f32_e32 v114, v130, v114
	v_bfe_u32 v115, v114, 16, 1
	v_add3_u32 v114, v114, v115, s30
	global_store_short_d16_hi v[4:5], v114, off offset:2240
	v_mul_f32_e32 v4, v137, v116
	v_mul_f32_e32 v4, v130, v4
	v_bfe_u32 v5, v4, 16, 1
	v_add3_u32 v114, v4, v5, s30
	v_lshl_add_u64 v[4:5], v[6:7], 0, v[8:9]
	global_store_short_d16_hi v[4:5], v114, off
	v_mul_f32_e32 v4, v141, v117
	v_mul_f32_e32 v4, v130, v4
	v_bfe_u32 v5, v4, 16, 1
	v_add3_u32 v8, v4, v5, s30
	v_lshl_add_u64 v[4:5], v[6:7], 0, v[10:11]
	global_store_short_d16_hi v[4:5], v8, off
	v_mul_f32_e32 v4, v144, v119
	v_mul_f32_e32 v4, v130, v4
	v_bfe_u32 v5, v4, 16, 1
	v_add3_u32 v8, v4, v5, s30
	v_lshl_add_u64 v[4:5], v[6:7], 0, v[12:13]
	global_store_short_d16_hi v[4:5], v8, off
	v_mul_f32_e32 v4, v147, v118
	v_mul_f32_e32 v4, v130, v4
	v_bfe_u32 v5, v4, 16, 1
	v_add3_u32 v8, v4, v5, s30
	v_lshl_add_u64 v[4:5], v[6:7], 0, v[14:15]
	global_store_short_d16_hi v[4:5], v8, off
	v_mul_f32_e32 v4, v148, v120
	v_mul_f32_e32 v4, v130, v4
	v_bfe_u32 v5, v4, 16, 1
	v_add3_u32 v8, v4, v5, s30
	v_lshl_add_u64 v[4:5], v[6:7], 0, v[80:81]
	global_store_short_d16_hi v[4:5], v8, off
	v_mul_f32_e32 v4, v150, v121
	v_mul_f32_e32 v4, v130, v4
	v_bfe_u32 v5, v4, 16, 1
	v_add3_u32 v8, v4, v5, s30
	v_lshl_add_u64 v[4:5], v[6:7], 0, v[82:83]
	global_store_short_d16_hi v[4:5], v8, off
	v_mul_f32_e32 v4, v153, v123
	v_mul_f32_e32 v4, v130, v4
	v_bfe_u32 v5, v4, 16, 1
	v_add3_u32 v8, v4, v5, s30
	v_lshl_add_u64 v[4:5], v[6:7], 0, v[84:85]
	global_store_short_d16_hi v[4:5], v8, off
	v_mul_f32_e32 v4, v156, v122
	v_mul_f32_e32 v4, v130, v4
	v_bfe_u32 v5, v4, 16, 1
	v_add3_u32 v8, v4, v5, s30
	v_lshl_add_u64 v[4:5], v[6:7], 0, v[86:87]
	global_store_short_d16_hi v[4:5], v8, off
	v_mul_f32_e32 v4, v159, v124
	v_mul_f32_e32 v4, v130, v4
	v_bfe_u32 v5, v4, 16, 1
	v_add3_u32 v8, v4, v5, s30
	v_lshl_add_u64 v[4:5], v[6:7], 0, v[88:89]
	global_store_short_d16_hi v[4:5], v8, off
	v_mul_f32_e32 v4, v160, v125
	v_mul_f32_e32 v4, v130, v4
	v_bfe_u32 v5, v4, 16, 1
	v_add3_u32 v8, v4, v5, s30
	v_lshl_add_u64 v[4:5], v[6:7], 0, v[90:91]
	global_store_short_d16_hi v[4:5], v8, off
	v_mul_f32_e32 v4, v161, v127
	v_mul_f32_e32 v4, v130, v4
	v_bfe_u32 v5, v4, 16, 1
	v_add3_u32 v8, v4, v5, s30
	v_lshl_add_u64 v[4:5], v[6:7], 0, v[92:93]
	global_store_short_d16_hi v[4:5], v8, off
	v_mul_f32_e32 v4, v162, v126
	v_mul_f32_e32 v4, v130, v4
	v_bfe_u32 v5, v4, 16, 1
	v_add3_u32 v8, v4, v5, s30
	v_lshl_add_u64 v[4:5], v[6:7], 0, v[94:95]
	global_store_short_d16_hi v[4:5], v8, off
	v_mul_f32_e32 v4, v163, v128
	v_mul_f32_e32 v4, v130, v4
	v_bfe_u32 v5, v4, 16, 1
	v_add3_u32 v8, v4, v5, s30
	v_lshl_add_u64 v[4:5], v[6:7], 0, v[96:97]
	global_store_short_d16_hi v[4:5], v8, off
	v_mul_f32_e32 v4, v165, v129
	v_mul_f32_e32 v4, v130, v4
	v_bfe_u32 v5, v4, 16, 1
	v_add3_u32 v8, v4, v5, s30
	v_lshl_add_u64 v[4:5], v[6:7], 0, v[2:3]
	global_store_short_d16_hi v[4:5], v8, off
